# plain exp2 (no below-2^-126 scaling wrapper) also in the attention unit's last-tile block; otherwise the previous version
# speedup vs baseline: 1.0053x; 1.0012x over previous
.LBB0_795:
	s_nop 8
	v_max_f32_e32 v64, v32, v32
	v_max_f32_e32 v65, v48, v48
	v_max_f32_e32 v64, v65, v64
	v_max3_f32 v64, v64, v49, v33
	v_max3_f32 v64, v64, v50, v34
	v_max3_f32 v64, v64, v51, v35
	v_max3_f32 v64, v64, v52, v36
	v_max3_f32 v64, v64, v53, v37
	v_max3_f32 v64, v64, v54, v38
	v_max3_f32 v64, v64, v55, v39
	v_max3_f32 v64, v64, v56, v40
	v_max3_f32 v64, v64, v57, v41
	v_max3_f32 v64, v64, v58, v42
	v_max3_f32 v64, v64, v59, v43
	v_max3_f32 v64, v64, v60, v44
	v_max3_f32 v64, v64, v61, v45
	v_max3_f32 v64, v64, v62, v46
	v_max3_f32 v64, v64, v63, v47
	ds_bpermute_b32 v65, v191, v64
	v_add_u32_e32 v84, v203, v204
	s_waitcnt lgkmcnt(0)
	v_max3_f32 v67, v195, v64, v65
	v_sub_f32_e32 v48, v48, v67
	v_sub_f32_e32 v32, v32, v67
	v_sub_f32_e32 v49, v49, v67
	v_exp_f32_e32 v32, v32
	v_exp_f32_e32 v64, v49
	v_mov_b32_e32 v49, v32
	v_mov_b32_e32 v64, v64
	v_sub_f32_e32 v32, v33, v67
	v_exp_f32_e32 v48, v48
	v_sub_f32_e32 v68, v195, v67
	v_sub_f32_e32 v33, v50, v67
	v_exp_f32_e32 v32, v32
	v_mov_b32_e32 v48, v48
	v_exp_f32_e32 v33, v33
	v_mov_b32_e32 v65, v32
	v_mov_b32_e32 v50, v33
	v_sub_f32_e32 v32, v34, v67
	v_sub_f32_e32 v46, v46, v67
	v_sub_f32_e32 v47, v47, v67
	v_sub_f32_e32 v33, v51, v67
	v_exp_f32_e32 v32, v32
	s_nop 0
	v_exp_f32_e32 v33, v33
	v_mov_b32_e32 v66, v32
	v_mov_b32_e32 v51, v33
	v_sub_f32_e32 v32, v35, v67
	s_nop 1
	v_sub_f32_e32 v33, v52, v67
	v_exp_f32_e32 v32, v32
	v_cvt_pk_bf16_f32 v52, v48, v64
	v_add_f32_e32 v48, v48, v49
	v_exp_f32_e32 v33, v33
	v_mov_b32_e32 v70, v32
	v_mov_b32_e32 v71, v33
	v_sub_f32_e32 v32, v36, v67
	s_nop 1
	v_sub_f32_e32 v33, v53, v67
	v_exp_f32_e32 v32, v32
	v_cvt_pk_bf16_f32 v53, v50, v51
	s_nop 0
	v_exp_f32_e32 v33, v33
	v_mov_b32_e32 v72, v32
	v_mov_b32_e32 v73, v33
	v_sub_f32_e32 v32, v37, v67
	s_nop 1
	v_sub_f32_e32 v33, v54, v67
	v_exp_f32_e32 v32, v32
	v_cvt_pk_bf16_f32 v54, v71, v73
	s_nop 0
	v_exp_f32_e32 v33, v33
	v_mov_b32_e32 v74, v32
	v_mov_b32_e32 v75, v33
	v_sub_f32_e32 v32, v38, v67
	s_nop 1
	v_sub_f32_e32 v33, v55, v67
	v_exp_f32_e32 v32, v32
	s_nop 0
	v_exp_f32_e32 v33, v33
	v_mov_b32_e32 v76, v32
	v_mov_b32_e32 v77, v33
	v_sub_f32_e32 v32, v39, v67
	v_cvt_pk_bf16_f32 v55, v75, v77
	s_nop 1
	v_sub_f32_e32 v33, v56, v67
	v_exp_f32_e32 v32, v32
	s_nop 0
	v_exp_f32_e32 v33, v33
	v_mov_b32_e32 v78, v32
	v_mov_b32_e32 v79, v33
	v_sub_f32_e32 v32, v40, v67
	s_nop 1
	v_sub_f32_e32 v33, v57, v67
	v_exp_f32_e32 v32, v32
	s_nop 0
	v_exp_f32_e32 v33, v33
	v_mov_b32_e32 v80, v32
	v_mov_b32_e32 v81, v33
	v_sub_f32_e32 v32, v41, v67
	s_nop 1
	v_sub_f32_e32 v33, v58, v67
	v_exp_f32_e32 v32, v32
	s_nop 0
	v_exp_f32_e32 v33, v33
	v_mov_b32_e32 v41, v32
	v_mov_b32_e32 v33, v33
	v_sub_f32_e32 v32, v42, v67
	s_nop 1
	v_sub_f32_e32 v34, v59, v67
	v_exp_f32_e32 v32, v32
	s_nop 0
	v_exp_f32_e32 v34, v34
	v_mov_b32_e32 v35, v32
	v_mov_b32_e32 v32, v34
	v_sub_f32_e32 v34, v43, v67
	s_nop 1
	v_sub_f32_e32 v36, v60, v67
	v_exp_f32_e32 v34, v34
	s_nop 0
	v_exp_f32_e32 v36, v36
	v_mov_b32_e32 v34, v34
	v_mov_b32_e32 v37, v36
	v_sub_f32_e32 v36, v44, v67
	s_waitcnt vmcnt(7)
	v_lshrrev_b32_e32 v44, 16, v124
	s_waitcnt vmcnt(5)
	v_and_or_b32 v44, v128, s31, v44
	v_sub_f32_e32 v38, v61, v67
	v_exp_f32_e32 v36, v36
	s_nop 0
	v_exp_f32_e32 v38, v38
	v_mov_b32_e32 v39, v36
	v_mov_b32_e32 v36, v38
	v_sub_f32_e32 v38, v45, v67
	s_nop 0
	v_sub_f32_e32 v40, v62, v67
	v_mov_b32_e32 v43, v68
	v_exp_f32_e32 v69, v40
	v_sub_f32_e32 v40, v63, v67
	v_exp_f32_e32 v43, v43
	v_mov_b32_e32 v69, v69
	v_exp_f32_e32 v68, v40
	v_and_b32_e32 v42, 0xffff, v124
	v_mov_b32_e32 v40, v43
	v_lshl_or_b32 v42, v128, 16, v42
	v_add_u32_e32 v43, v181, v224
	ds_write2_b32 v43, v42, v44 offset1:36
	v_and_b32_e32 v42, 0xffff, v125
	v_lshrrev_b32_e32 v44, 16, v125
	v_lshl_or_b32 v42, v129, 16, v42
	v_and_or_b32 v44, v129, s31, v44
	ds_write2_b32 v43, v42, v44 offset0:72 offset1:108
	v_and_b32_e32 v42, 0xffff, v126
	v_lshrrev_b32_e32 v44, 16, v126
	v_lshl_or_b32 v42, v130, 16, v42
	v_and_or_b32 v44, v130, s31, v44
	ds_write2_b32 v43, v42, v44 offset0:144 offset1:180
	v_and_b32_e32 v42, 0xffff, v127
	v_lshrrev_b32_e32 v44, 16, v127
	v_lshl_or_b32 v42, v131, 16, v42
	v_and_or_b32 v44, v131, s31, v44
	ds_write2_b32 v43, v42, v44 offset0:216 offset1:252
	v_and_b32_e32 v42, 0xffff, v116
	v_lshrrev_b32_e32 v44, 16, v116
	s_waitcnt vmcnt(4)
	v_lshl_or_b32 v42, v120, 16, v42
	v_add_u32_e32 v43, v181, v225
	v_and_or_b32 v44, v120, s31, v44
	ds_write2_b32 v43, v42, v44 offset1:36
	v_and_b32_e32 v42, 0xffff, v117
	v_lshrrev_b32_e32 v44, 16, v117
	v_lshl_or_b32 v42, v121, 16, v42
	v_and_or_b32 v44, v121, s31, v44
	ds_write2_b32 v43, v42, v44 offset0:72 offset1:108
	v_and_b32_e32 v42, 0xffff, v118
	v_lshrrev_b32_e32 v44, 16, v118
	v_lshl_or_b32 v42, v122, 16, v42
	v_and_or_b32 v44, v122, s31, v44
	ds_write2_b32 v43, v42, v44 offset0:144 offset1:180
	v_and_b32_e32 v42, 0xffff, v119
	v_lshrrev_b32_e32 v44, 16, v119
	v_lshl_or_b32 v42, v123, 16, v42
	v_and_or_b32 v44, v123, s31, v44
	ds_write2_b32 v43, v42, v44 offset0:216 offset1:252
	s_waitcnt vmcnt(3)
	v_and_b32_e32 v42, 0xffff, v108
	v_lshrrev_b32_e32 v44, 16, v108
	s_waitcnt vmcnt(1)
	v_lshl_or_b32 v42, v112, 16, v42
	v_and_or_b32 v44, v112, s31, v44
	v_add_u32_e32 v45, 0x800, v43
	ds_write2_b32 v45, v42, v44 offset0:64 offset1:100
	v_and_b32_e32 v42, 0xffff, v109
	v_lshrrev_b32_e32 v44, 16, v109
	v_lshl_or_b32 v42, v113, 16, v42
	v_and_or_b32 v44, v113, s31, v44
	ds_write2_b32 v45, v42, v44 offset0:136 offset1:172
	v_and_b32_e32 v42, 0xffff, v110
	v_lshrrev_b32_e32 v44, 16, v110
	v_lshl_or_b32 v42, v114, 16, v42
	v_and_or_b32 v44, v114, s31, v44
	ds_write2_b32 v45, v42, v44 offset0:208 offset1:244
	v_and_b32_e32 v42, 0xffff, v111
	v_lshrrev_b32_e32 v44, 16, v111
	v_lshl_or_b32 v42, v115, 16, v42
	v_and_or_b32 v44, v115, s31, v44
	v_add_u32_e32 v45, 0xc00, v43
	ds_write2_b32 v45, v42, v44 offset0:24 offset1:60
	v_and_b32_e32 v42, 0xffff, v100
	v_lshrrev_b32_e32 v44, 16, v100
	s_waitcnt vmcnt(0)
	v_lshl_or_b32 v42, v104, 16, v42
	v_and_or_b32 v44, v104, s31, v44
	v_add_u32_e32 v45, 0x1000, v43
	ds_write2_b32 v45, v42, v44 offset0:128 offset1:164
	v_and_b32_e32 v42, 0xffff, v101
	v_lshrrev_b32_e32 v44, 16, v101
	v_lshl_or_b32 v42, v105, 16, v42
	v_and_or_b32 v44, v105, s31, v44
	ds_write2_b32 v45, v42, v44 offset0:200 offset1:236
	v_and_b32_e32 v42, 0xffff, v102
	v_lshrrev_b32_e32 v44, 16, v102
	v_lshl_or_b32 v42, v106, 16, v42
	v_and_or_b32 v44, v106, s31, v44
	v_add_u32_e32 v43, 0x1400, v43
	ds_write2_b32 v43, v42, v44 offset0:16 offset1:52
	v_and_b32_e32 v42, 0xffff, v103
	v_lshrrev_b32_e32 v44, 16, v103
	v_lshl_or_b32 v42, v107, 16, v42
	v_and_or_b32 v44, v107, s31, v44
	ds_write2_b32 v43, v42, v44 offset0:88 offset1:124
	s_waitcnt lgkmcnt(0)
	ds_read_b128 v[42:45], v84
	ds_read_b128 v[56:59], v84 offset:32
	ds_read_b128 v[60:63], v84 offset:4608
	v_pk_mul_f32 v[30:31], v[30:31], v[40:41] op_sel_hi:[1,0]
	v_pk_mul_f32 v[28:29], v[28:29], v[40:41] op_sel_hi:[1,0]
	v_pk_mul_f32 v[26:27], v[26:27], v[40:41] op_sel_hi:[1,0]
	v_pk_mul_f32 v[24:25], v[24:25], v[40:41] op_sel_hi:[1,0]
	v_pk_mul_f32 v[22:23], v[22:23], v[40:41] op_sel_hi:[1,0]
	v_pk_mul_f32 v[20:21], v[20:21], v[40:41] op_sel_hi:[1,0]
	v_pk_mul_f32 v[18:19], v[18:19], v[40:41] op_sel_hi:[1,0]
	v_pk_mul_f32 v[16:17], v[16:17], v[40:41] op_sel_hi:[1,0]
	v_pk_mul_f32 v[14:15], v[14:15], v[40:41] op_sel_hi:[1,0]
	v_pk_mul_f32 v[12:13], v[12:13], v[40:41] op_sel_hi:[1,0]
	s_waitcnt lgkmcnt(2)
	v_mfma_f32_32x32x16_bf16 v[16:31], v[42:45], v[52:55], v[16:31]
	v_mul_f32_e64 v10, v10, v40
	v_mul_f32_e64 v11, v11, v40
	v_mul_f32_e64 v8, v8, v40
	v_mul_f32_e64 v9, v9, v40
	v_mul_f32_e64 v6, v6, v40
	v_mul_f32_e64 v7, v7, v40
	v_pk_mul_f32 v[4:5], v[4:5], v[40:41] op_sel_hi:[1,0]
	v_pk_mul_f32 v[2:3], v[2:3], v[40:41] op_sel_hi:[1,0]
	v_pk_mul_f32 v[0:1], v[0:1], v[40:41] op_sel_hi:[1,0]
	ds_read_b128 v[42:45], v84 offset:4640
	s_nop 0
	s_waitcnt lgkmcnt(1)
	v_mfma_f32_32x32x16_bf16 v[0:15], v[60:63], v[52:55], v[0:15]
	v_mov_b32_e32 v68, v68
	v_cvt_pk_bf16_f32 v52, v79, v81
	v_cvt_pk_bf16_f32 v53, v33, v32
	v_cvt_pk_bf16_f32 v54, v37, v36
	v_cvt_pk_bf16_f32 v55, v69, v68
	s_nop 0
	s_waitcnt lgkmcnt(0)
	v_mfma_f32_32x32x16_bf16 v[0:15], v[42:45], v[52:55], v[0:15]
	ds_read_b128 v[42:45], v84 offset:64
	v_exp_f32_e32 v38, v38
	s_nop 0
	v_pk_add_f32 v[32:33], v[32:33], v[34:35]
	v_mov_b32_e32 v38, v38
	v_mfma_f32_32x32x16_bf16 v[16:31], v[56:59], v[52:55], v[16:31]
	v_cvt_pk_bf16_f32 v52, v49, v65
	v_add_f32_e32 v49, v64, v65
	v_add_f32_e32 v48, v48, v49
	v_add_f32_e32 v49, v50, v66
	v_add_f32_e32 v48, v49, v48
	v_add_f32_e32 v49, v51, v70
	v_add_f32_e32 v48, v49, v48
	v_add_f32_e32 v49, v71, v72
	ds_read_b128 v[56:59], v84 offset:4672
	ds_read_b128 v[60:63], v84 offset:96
	v_add_f32_e32 v48, v49, v48
	v_add_f32_e32 v49, v73, v74
	v_add_f32_e32 v48, v49, v48
	v_add_f32_e32 v49, v75, v76
	v_add_f32_e32 v48, v49, v48
	v_add_f32_e32 v49, v77, v78
	v_exp_f32_e32 v46, v46
	v_cvt_pk_bf16_f32 v53, v66, v70
	v_cvt_pk_bf16_f32 v54, v72, v74
	v_cvt_pk_bf16_f32 v55, v76, v78
	v_add_f32_e32 v48, v49, v48
	s_waitcnt lgkmcnt(2)
	v_mfma_f32_32x32x16_bf16 v[16:31], v[42:45], v[52:55], v[16:31]
	v_mov_b32_e32 v42, v47
	v_add_f32_e32 v49, v79, v80
	v_exp_f32_e32 v42, v42
	v_add_f32_e32 v48, v49, v48
	v_mov_b32_e32 v47, v46
	s_nop 0
	s_waitcnt lgkmcnt(1)
	v_mfma_f32_32x32x16_bf16 v[0:15], v[56:59], v[52:55], v[0:15]
	v_cvt_pk_bf16_f32 v52, v80, v41
	v_add_f32_e32 v41, v81, v41
	v_add_f32_e32 v41, v41, v48
	v_add_f32_e32 v33, v33, v41
	v_cvt_pk_bf16_f32 v53, v35, v34
	v_add_f32_e32 v34, v32, v33
	v_add_f32_e64 v32, v36, v38
	v_add_f32_e64 v33, v37, v39
	v_mov_b32_e32 v46, v42
	v_add_f32_e32 v33, v33, v34
	v_add_f32_e32 v34, v32, v33
	v_pk_add_f32 v[32:33], v[68:69], v[46:47]
	ds_read_b128 v[42:45], v84 offset:4704
	v_add_f32_e32 v33, v33, v34
	v_add_f32_e32 v32, v32, v33
	v_fmac_f32_e32 v32, v144, v40
	ds_bpermute_b32 v33, v191, v32
	v_cvt_pk_bf16_f32 v54, v39, v38
	v_cvt_pk_bf16_f32 v55, v47, v46
	v_mov_b32_e32 v191, v183
	s_waitcnt lgkmcnt(1)
	v_mfma_f32_32x32x16_bf16 v[0:15], v[42:45], v[52:55], v[0:15]
	s_waitcnt lgkmcnt(0)
	v_add_f32_e32 v32, v32, v33
	v_div_scale_f32 v33, s[12:13], v32, v32, 1.0
	v_rcp_f32_e32 v34, v33
	s_waitcnt lgkmcnt(0)
	s_mov_b64 s[12:13], 0
	v_fma_f32 v35, -v33, v34, 1.0
	v_fmac_f32_e32 v34, v35, v34
	v_div_scale_f32 v35, vcc, 1.0, v32, 1.0
	v_mul_f32_e32 v36, v35, v34
	v_mfma_f32_32x32x16_bf16 v[16:31], v[60:63], v[52:55], v[16:31]
	v_fma_f32 v37, -v33, v36, v35
	v_fmac_f32_e32 v36, v37, v34
	v_fma_f32 v33, -v33, v36, v35
	v_div_fmas_f32 v33, v33, v34, v36
	v_div_fixup_f32 v34, v33, v32, 1.0
	v_mul_f32_e32 v0, v0, v34
	v_mul_f32_e32 v1, v1, v34
	v_cvt_pk_bf16_f32 v0, v0, v1
	v_mul_f32_e32 v1, v2, v34
	v_lshl_add_u64 v[32:33], v[192:193], 0, v[190:191]
	v_mul_f32_e32 v2, v3, v34
	v_cvt_pk_bf16_f32 v1, v1, v2
	global_store_dwordx2 v[32:33], v[0:1], off offset:64
	s_nop 0
	v_mul_f32_e32 v0, v20, v34
	v_mul_f32_e32 v1, v21, v34
	v_cvt_pk_bf16_f32 v0, v0, v1
	v_mul_f32_e32 v1, v22, v34
	v_mul_f32_e32 v2, v23, v34
	v_cvt_pk_bf16_f32 v1, v1, v2
	global_store_dwordx2 v[32:33], v[0:1], off offset:16
	v_mul_f32_e32 v0, v4, v34
	v_mul_f32_e32 v1, v5, v34
	v_cvt_pk_bf16_f32 v0, v0, v1
	v_mul_f32_e32 v1, v6, v34
	v_mul_f32_e32 v2, v7, v34
	v_cvt_pk_bf16_f32 v1, v1, v2
	global_store_dwordx2 v[32:33], v[0:1], off offset:80
	v_mul_f32_e32 v0, v24, v34
	v_mul_f32_e32 v1, v25, v34
	v_cvt_pk_bf16_f32 v0, v0, v1
	v_mul_f32_e32 v1, v26, v34
	v_mul_f32_e32 v2, v27, v34
	v_cvt_pk_bf16_f32 v1, v1, v2
	global_store_dwordx2 v[32:33], v[0:1], off offset:32
	v_mul_f32_e32 v0, v8, v34
	v_mul_f32_e32 v1, v9, v34
	v_cvt_pk_bf16_f32 v0, v0, v1
	v_mul_f32_e32 v1, v10, v34
	v_mul_f32_e32 v2, v11, v34
	v_cvt_pk_bf16_f32 v1, v1, v2
	global_store_dwordx2 v[32:33], v[0:1], off offset:96
	v_mul_f32_e32 v0, v28, v34
	v_mul_f32_e32 v1, v29, v34
	v_cvt_pk_bf16_f32 v0, v0, v1
	v_mul_f32_e32 v1, v30, v34
	v_mul_f32_e32 v2, v31, v34
	v_cvt_pk_bf16_f32 v1, v1, v2
	v_mul_f32_e32 v16, v16, v34
	v_mul_f32_e32 v17, v17, v34
	global_store_dwordx2 v[32:33], v[0:1], off offset:48
	v_mul_f32_e32 v0, v12, v34
	v_mul_f32_e32 v1, v13, v34
	v_cvt_pk_bf16_f32 v16, v16, v17
	v_mul_f32_e32 v17, v18, v34
	v_cvt_pk_bf16_f32 v0, v0, v1
	v_mul_f32_e32 v1, v14, v34
	v_mul_f32_e32 v18, v19, v34
	v_cvt_pk_bf16_f32 v17, v17, v18
	global_store_dwordx2 v[32:33], v[16:17], off
	v_mul_f32_e32 v2, v15, v34
	v_cvt_pk_bf16_f32 v1, v1, v2
	global_store_dwordx2 v[32:33], v[0:1], off offset:112
